# EpiResidual pipelining plus compress_item MLP loops hand-pipelined (rotating one-iteration-deep prefetch with counted vmcnt instead of two serialized round trips per 16-wide K step)
# speedup vs baseline: 1.0071x; 1.0071x over previous
.LBB0_994:
	s_waitcnt lgkmcnt(0)
	s_barrier
	ds_read_b32 v0, v28
	s_movk_i32 s63, 0x7f
	s_mov_b64 s[64:65], -1
	s_waitcnt lgkmcnt(0)
	v_cmp_lt_i32_e32 vcc, s63, v0
	v_readfirstlane_b32 s14, v0
	s_cbranch_vccnz .LBB0_987
	s_lshl_b32 s63, s14, 5
	v_mbcnt_lo_u32_b32 v0, -1, 0
	v_mbcnt_hi_u32_b32 v0, -1, v0
	s_and_b32 s63, s63, 0x7e0
	v_and_b32_e32 v31, 31, v0
	v_ashrrev_i32_e32 v32, 5, v0
	v_or_b32_e32 v0, s63, v31
	v_min_u32_e32 v0, 0x7ef, v0
	v_lshrrev_b16_e32 v1, 1, v0
	v_mul_u32_u24_e32 v1, 0x8103, v1
	v_lshrrev_b32_e32 v1, 22, v1
	s_cmp_lt_u32 s14, 64
	v_mul_lo_u16_e32 v2, 0xfe, v1
	s_cselect_b64 s[64:65], -1, 0
	v_sub_u16_e32 v2, v0, v2
	s_and_b64 s[66:67], s[64:65], exec
	v_lshlrev_b16_e32 v0, 11, v1
	v_lshlrev_b32_e32 v1, 3, v2
	v_and_or_b32 v0, v1, s29, v0
	v_lshlrev_b32_e32 v18, 3, v32
	s_cselect_b32 s66, s9, s13
	s_cselect_b32 s67, s8, s12
	v_mul_u32_u24_e32 v4, 0xd00, v0
	v_ashrrev_i32_e32 v19, 31, v18
	v_mov_b32_e32 v0, s67
	v_mov_b32_e32 v1, s66
	s_movk_i32 s66, 0x1200
	v_lshl_add_u64 v[20:21], v[18:19], 2, v[0:1]
	v_and_b32_e32 v0, 1, v2
	s_cselect_b32 s66, s66, 0x1300
	v_lshl_or_b32 v16, v0, 7, s66
	v_lshlrev_b64 v[0:1], 1, v[18:19]
	v_lshl_add_u64 v[2:3], v[16:17], 0, v[0:1]
	v_lshlrev_b32_e32 v16, 1, v4
	s_mov_b32 s14, 0x7288000
	v_lshl_add_u64 v[2:3], v[2:3], 0, v[16:17]
	v_add_u32_e32 v16, s47, v31
	s_cselect_b32 s14, s14, 0x7388000
	v_lshl_add_u64 v[22:23], s[18:19], 0, v[2:3]
	v_lshlrev_b64 v[2:3], 12, v[16:17]
	v_lshl_add_u64 v[2:3], s[14:15], 0, v[2:3]
	v_lshl_add_u64 v[0:1], v[2:3], 0, v[0:1]
	v_lshl_add_u64 v[24:25], s[20:21], 0, v[0:1]
	v_mov_b32_e32 v0, 0
	s_mov_b64 s[66:67], 0
	v_mov_b32_e32 v1, v0
	v_mov_b32_e32 v2, v0
	v_mov_b32_e32 v3, v0
	v_mov_b32_e32 v4, v0
	v_mov_b32_e32 v5, v0
	v_mov_b32_e32 v6, v0
	v_mov_b32_e32 v7, v0
	v_mov_b32_e32 v8, v0
	v_mov_b32_e32 v9, v0
	v_mov_b32_e32 v10, v0
	v_mov_b32_e32 v11, v0
	v_mov_b32_e32 v12, v0
	v_mov_b32_e32 v13, v0
	v_mov_b32_e32 v14, v0
	v_mov_b32_e32 v15, v0
	v_lshl_add_u64 v[26:27], v[20:21], 0, s[66:67]
	global_load_dwordx4 v[140:143], v[22:23], off offset:-64
	global_load_dwordx4 v[144:147], v[26:27], off offset:16
	global_load_dwordx4 v[148:151], v[26:27], off
	global_load_dwordx4 v[152:155], v[24:25], off offset:-64
	global_load_dwordx4 v[156:159], v[22:23], off offset:-32
	global_load_dwordx4 v[160:163], v[26:27], off offset:80
	global_load_dwordx4 v[164:167], v[26:27], off offset:64
	global_load_dwordx4 v[168:171], v[24:25], off offset:-32
	global_load_dwordx4 v[172:175], v[22:23], off
	global_load_dwordx4 v[176:179], v[26:27], off offset:144
	global_load_dwordx4 v[180:183], v[26:27], off offset:128
	global_load_dwordx4 v[184:187], v[24:25], off
	global_load_dwordx4 v[188:191], v[22:23], off offset:32
	global_load_dwordx4 v[192:195], v[26:27], off offset:208
	global_load_dwordx4 v[196:199], v[26:27], off offset:192
	global_load_dwordx4 v[200:203], v[24:25], off offset:32
.Lcmp_k_loop:
	s_mov_b64 s[68:69], 0x1a00
	v_lshl_add_u64 v[22:23], v[22:23], 0, s[68:69]
	s_mov_b64 s[68:69], 0x80
	v_lshl_add_u64 v[24:25], v[24:25], 0, s[68:69]
	s_add_u32 s66, s66, 0x100
	s_addc_u32 s67, s67, 0
	v_lshl_add_u64 v[26:27], v[20:21], 0, s[66:67]
	s_waitcnt vmcnt(12)
	v_lshlrev_b32_e32 v16, 16, v140
	v_and_b32_e32 v33, 0xffff0000, v140
	v_add_f32_e32 v16, v148, v16
	v_add_f32_e32 v33, v149, v33
	v_cvt_pk_bf16_f32 v140, v16, v33
	v_lshlrev_b32_e32 v16, 16, v141
	v_and_b32_e32 v33, 0xffff0000, v141
	v_add_f32_e32 v16, v150, v16
	v_add_f32_e32 v33, v151, v33
	v_cvt_pk_bf16_f32 v141, v16, v33
	v_lshlrev_b32_e32 v16, 16, v142
	v_and_b32_e32 v33, 0xffff0000, v142
	v_add_f32_e32 v16, v144, v16
	v_add_f32_e32 v33, v145, v33
	v_cvt_pk_bf16_f32 v142, v16, v33
	v_lshlrev_b32_e32 v16, 16, v143
	v_and_b32_e32 v33, 0xffff0000, v143
	v_add_f32_e32 v16, v146, v16
	v_add_f32_e32 v33, v147, v33
	v_cvt_pk_bf16_f32 v143, v16, v33
	s_nop 1
	v_mfma_f32_32x32x16_bf16 v[0:15], v[140:143], v[152:155], v[0:15]
	global_load_dwordx4 v[140:143], v[22:23], off offset:-64
	global_load_dwordx4 v[144:147], v[26:27], off offset:16
	global_load_dwordx4 v[148:151], v[26:27], off
	global_load_dwordx4 v[152:155], v[24:25], off offset:-64
	s_waitcnt vmcnt(12)
	v_lshlrev_b32_e32 v16, 16, v156
	v_and_b32_e32 v33, 0xffff0000, v156
	v_add_f32_e32 v16, v164, v16
	v_add_f32_e32 v33, v165, v33
	v_cvt_pk_bf16_f32 v156, v16, v33
	v_lshlrev_b32_e32 v16, 16, v157
	v_and_b32_e32 v33, 0xffff0000, v157
	v_add_f32_e32 v16, v166, v16
	v_add_f32_e32 v33, v167, v33
	v_cvt_pk_bf16_f32 v157, v16, v33
	v_lshlrev_b32_e32 v16, 16, v158
	v_and_b32_e32 v33, 0xffff0000, v158
	v_add_f32_e32 v16, v160, v16
	v_add_f32_e32 v33, v161, v33
	v_cvt_pk_bf16_f32 v158, v16, v33
	v_lshlrev_b32_e32 v16, 16, v159
	v_and_b32_e32 v33, 0xffff0000, v159
	v_add_f32_e32 v16, v162, v16
	v_add_f32_e32 v33, v163, v33
	v_cvt_pk_bf16_f32 v159, v16, v33
	s_nop 1
	v_mfma_f32_32x32x16_bf16 v[0:15], v[156:159], v[168:171], v[0:15]
	global_load_dwordx4 v[156:159], v[22:23], off offset:-32
	global_load_dwordx4 v[160:163], v[26:27], off offset:80
	global_load_dwordx4 v[164:167], v[26:27], off offset:64
	global_load_dwordx4 v[168:171], v[24:25], off offset:-32
	s_waitcnt vmcnt(12)
	v_lshlrev_b32_e32 v16, 16, v172
	v_and_b32_e32 v33, 0xffff0000, v172
	v_add_f32_e32 v16, v180, v16
	v_add_f32_e32 v33, v181, v33
	v_cvt_pk_bf16_f32 v172, v16, v33
	v_lshlrev_b32_e32 v16, 16, v173
	v_and_b32_e32 v33, 0xffff0000, v173
	v_add_f32_e32 v16, v182, v16
	v_add_f32_e32 v33, v183, v33
	v_cvt_pk_bf16_f32 v173, v16, v33
	v_lshlrev_b32_e32 v16, 16, v174
	v_and_b32_e32 v33, 0xffff0000, v174
	v_add_f32_e32 v16, v176, v16
	v_add_f32_e32 v33, v177, v33
	v_cvt_pk_bf16_f32 v174, v16, v33
	v_lshlrev_b32_e32 v16, 16, v175
	v_and_b32_e32 v33, 0xffff0000, v175
	v_add_f32_e32 v16, v178, v16
	v_add_f32_e32 v33, v179, v33
	v_cvt_pk_bf16_f32 v175, v16, v33
	s_nop 1
	v_mfma_f32_32x32x16_bf16 v[0:15], v[172:175], v[184:187], v[0:15]
	global_load_dwordx4 v[172:175], v[22:23], off
	global_load_dwordx4 v[176:179], v[26:27], off offset:144
	global_load_dwordx4 v[180:183], v[26:27], off offset:128
	global_load_dwordx4 v[184:187], v[24:25], off
	s_waitcnt vmcnt(12)
	v_lshlrev_b32_e32 v16, 16, v188
	v_and_b32_e32 v33, 0xffff0000, v188
	v_add_f32_e32 v16, v196, v16
	v_add_f32_e32 v33, v197, v33
	v_cvt_pk_bf16_f32 v188, v16, v33
	v_lshlrev_b32_e32 v16, 16, v189
	v_and_b32_e32 v33, 0xffff0000, v189
	v_add_f32_e32 v16, v198, v16
	v_add_f32_e32 v33, v199, v33
	v_cvt_pk_bf16_f32 v189, v16, v33
	v_lshlrev_b32_e32 v16, 16, v190
	v_and_b32_e32 v33, 0xffff0000, v190
	v_add_f32_e32 v16, v192, v16
	v_add_f32_e32 v33, v193, v33
	v_cvt_pk_bf16_f32 v190, v16, v33
	v_lshlrev_b32_e32 v16, 16, v191
	v_and_b32_e32 v33, 0xffff0000, v191
	v_add_f32_e32 v16, v194, v16
	v_add_f32_e32 v33, v195, v33
	v_cvt_pk_bf16_f32 v191, v16, v33
	s_nop 1
	v_mfma_f32_32x32x16_bf16 v[0:15], v[188:191], v[200:203], v[0:15]
	global_load_dwordx4 v[188:191], v[22:23], off offset:32
	global_load_dwordx4 v[192:195], v[26:27], off offset:208
	global_load_dwordx4 v[196:199], v[26:27], off offset:192
	global_load_dwordx4 v[200:203], v[24:25], off offset:32
	s_cmpk_lg_i32 s66, 0x1f00
	s_cbranch_scc1 .Lcmp_k_loop
	s_waitcnt vmcnt(12)
	v_lshlrev_b32_e32 v16, 16, v140
	v_and_b32_e32 v33, 0xffff0000, v140
	v_add_f32_e32 v16, v148, v16
	v_add_f32_e32 v33, v149, v33
	v_cvt_pk_bf16_f32 v140, v16, v33
	v_lshlrev_b32_e32 v16, 16, v141
	v_and_b32_e32 v33, 0xffff0000, v141
	v_add_f32_e32 v16, v150, v16
	v_add_f32_e32 v33, v151, v33
	v_cvt_pk_bf16_f32 v141, v16, v33
	v_lshlrev_b32_e32 v16, 16, v142
	v_and_b32_e32 v33, 0xffff0000, v142
	v_add_f32_e32 v16, v144, v16
	v_add_f32_e32 v33, v145, v33
	v_cvt_pk_bf16_f32 v142, v16, v33
	v_lshlrev_b32_e32 v16, 16, v143
	v_and_b32_e32 v33, 0xffff0000, v143
	v_add_f32_e32 v16, v146, v16
	v_add_f32_e32 v33, v147, v33
	v_cvt_pk_bf16_f32 v143, v16, v33
	s_nop 1
	v_mfma_f32_32x32x16_bf16 v[0:15], v[140:143], v[152:155], v[0:15]
	s_waitcnt vmcnt(8)
	v_lshlrev_b32_e32 v16, 16, v156
	v_and_b32_e32 v33, 0xffff0000, v156
	v_add_f32_e32 v16, v164, v16
	v_add_f32_e32 v33, v165, v33
	v_cvt_pk_bf16_f32 v156, v16, v33
	v_lshlrev_b32_e32 v16, 16, v157
	v_and_b32_e32 v33, 0xffff0000, v157
	v_add_f32_e32 v16, v166, v16
	v_add_f32_e32 v33, v167, v33
	v_cvt_pk_bf16_f32 v157, v16, v33
	v_lshlrev_b32_e32 v16, 16, v158
	v_and_b32_e32 v33, 0xffff0000, v158
	v_add_f32_e32 v16, v160, v16
	v_add_f32_e32 v33, v161, v33
	v_cvt_pk_bf16_f32 v158, v16, v33
	v_lshlrev_b32_e32 v16, 16, v159
	v_and_b32_e32 v33, 0xffff0000, v159
	v_add_f32_e32 v16, v162, v16
	v_add_f32_e32 v33, v163, v33
	v_cvt_pk_bf16_f32 v159, v16, v33
	s_nop 1
	v_mfma_f32_32x32x16_bf16 v[0:15], v[156:159], v[168:171], v[0:15]
	s_waitcnt vmcnt(4)
	v_lshlrev_b32_e32 v16, 16, v172
	v_and_b32_e32 v33, 0xffff0000, v172
	v_add_f32_e32 v16, v180, v16
	v_add_f32_e32 v33, v181, v33
	v_cvt_pk_bf16_f32 v172, v16, v33
	v_lshlrev_b32_e32 v16, 16, v173
	v_and_b32_e32 v33, 0xffff0000, v173
	v_add_f32_e32 v16, v182, v16
	v_add_f32_e32 v33, v183, v33
	v_cvt_pk_bf16_f32 v173, v16, v33
	v_lshlrev_b32_e32 v16, 16, v174
	v_and_b32_e32 v33, 0xffff0000, v174
	v_add_f32_e32 v16, v176, v16
	v_add_f32_e32 v33, v177, v33
	v_cvt_pk_bf16_f32 v174, v16, v33
	v_lshlrev_b32_e32 v16, 16, v175
	v_and_b32_e32 v33, 0xffff0000, v175
	v_add_f32_e32 v16, v178, v16
	v_add_f32_e32 v33, v179, v33
	v_cvt_pk_bf16_f32 v175, v16, v33
	s_nop 1
	v_mfma_f32_32x32x16_bf16 v[0:15], v[172:175], v[184:187], v[0:15]
	s_waitcnt vmcnt(0)
	v_lshlrev_b32_e32 v16, 16, v188
	v_and_b32_e32 v33, 0xffff0000, v188
	v_add_f32_e32 v16, v196, v16
	v_add_f32_e32 v33, v197, v33
	v_cvt_pk_bf16_f32 v188, v16, v33
	v_lshlrev_b32_e32 v16, 16, v189
	v_and_b32_e32 v33, 0xffff0000, v189
	v_add_f32_e32 v16, v198, v16
	v_add_f32_e32 v33, v199, v33
	v_cvt_pk_bf16_f32 v189, v16, v33
	v_lshlrev_b32_e32 v16, 16, v190
	v_and_b32_e32 v33, 0xffff0000, v190
	v_add_f32_e32 v16, v192, v16
	v_add_f32_e32 v33, v193, v33
	v_cvt_pk_bf16_f32 v190, v16, v33
	v_lshlrev_b32_e32 v16, 16, v191
	v_and_b32_e32 v33, 0xffff0000, v191
	v_add_f32_e32 v16, v194, v16
	v_add_f32_e32 v33, v195, v33
	v_cvt_pk_bf16_f32 v191, v16, v33
	s_nop 1
	v_mfma_f32_32x32x16_bf16 v[0:15], v[188:191], v[200:203], v[0:15]
	s_nop 1
	s_nop 10
	v_mul_f32_e32 v16, 0x3d372713, v0
	v_mul_f32_e32 v16, v0, v16
	v_fma_f32 v16, v0, v16, v0
	v_mul_f32_e32 v16, 0x3f4c422a, v16
	v_cmp_nlt_f32_e64 s[66:67], |v16|, s30
	s_and_saveexec_b64 s[68:69], s[66:67]
	s_xor_b64 s[66:67], exec, s[68:69]
	s_cbranch_execz .LBB0_999
	v_add_f32_e64 v20, |v16|, |v16|
	v_mul_f32_e32 v21, 0x3fb8aa3b, v20
	v_rndne_f32_e32 v22, v21
	v_sub_f32_e32 v23, v21, v22
	v_fma_f32 v21, v20, s34, -v21
	v_fmac_f32_e32 v21, 0x32a5705f, v20
	v_add_f32_e32 v21, v23, v21
	v_cvt_i32_f32_e32 v22, v22
	v_exp_f32_e32 v21, v21
	v_cmp_ngt_f32_e32 vcc, s35, v20
	v_ldexp_f32 v21, v21, v22
	s_nop 0
	v_cndmask_b32_e32 v21, 0, v21, vcc
	v_cmp_nlt_f32_e32 vcc, s46, v20
	s_nop 1
	v_cndmask_b32_e32 v20, v30, v21, vcc
	v_add_f32_e32 v20, 1.0, v20
	v_rcp_f32_e32 v20, v20
	s_nop 0
	v_fma_f32 v20, v20, -2.0, 1.0

.LBB0_1059:
	s_andn2_saveexec_b64 s[66:67], s[66:67]
	v_mul_f32_e32 v2, v1, v1
	v_fmamk_f32 v3, v2, 0xbbbac73d, v29
	v_fmaak_f32 v3, v2, v3, 0xbd5c1c4e
	v_fmaak_f32 v3, v2, v3, 0x3e088382
	v_fmaak_f32 v3, v2, v3, 0xbeaaaa99
	v_mul_f32_e64 v3, |v1|, v3
	v_fma_f32 v2, v2, v3, |v1|
	s_or_b64 exec, exec, s[66:67]
	v_bfi_b32 v1, s56, v2, v1
	v_mul_f32_e32 v3, 0.5, v15
	v_add_f32_e32 v1, 1.0, v1
	v_mul_f32_e32 v1, v3, v1
	v_cvt_pk_bf16_f32 v1, v1, s0
	s_and_b64 vcc, exec, s[16:17]
	ds_write_b16 v0, v1 offset:14256
	s_waitcnt lgkmcnt(0)
	s_barrier
	s_cbranch_vccz .LBB0_986
	s_and_b64 s[66:67], s[64:65], exec
	s_mov_b32 s14, 0x488000
	s_cselect_b32 s14, s14, 0x4c8000
	s_add_u32 s66, s24, s14
	s_addc_u32 s67, s25, 0
	s_and_b64 s[64:65], s[64:65], exec
	s_mov_b32 s14, 0x7488000
	s_cselect_b32 s14, s14, 0x7490000
	s_add_u32 s64, s24, s14
	v_or_b32_e32 v16, s47, v31
	v_mul_u32_u24_e32 v0, 0x210, v31
	v_lshlrev_b32_e32 v1, 1, v18
	s_addc_u32 s65, s25, 0
	v_add3_u32 v33, 0, v0, v1
	v_lshlrev_b64 v[0:1], 9, v[16:17]
	v_lshl_add_u64 v[0:1], s[64:65], 0, v[0:1]
	v_lshl_add_u64 v[18:19], v[18:19], 1, v[0:1]
	global_load_dwordx4 v[140:143], v[18:19], off
	global_load_dwordx4 v[144:147], v[18:19], off offset:32
	global_load_dwordx4 v[148:151], v[18:19], off offset:64
	global_load_dwordx4 v[152:155], v[18:19], off offset:96
	global_load_dwordx4 v[156:159], v[18:19], off offset:128
	global_load_dwordx4 v[160:163], v[18:19], off offset:160
	global_load_dwordx4 v[164:167], v[18:19], off offset:192
	global_load_dwordx4 v[168:171], v[18:19], off offset:224
	global_load_dwordx4 v[172:175], v[18:19], off offset:256
	global_load_dwordx4 v[176:179], v[18:19], off offset:288
	global_load_dwordx4 v[180:183], v[18:19], off offset:320
	global_load_dwordx4 v[184:187], v[18:19], off offset:352
	global_load_dwordx4 v[188:191], v[18:19], off offset:384
	global_load_dwordx4 v[192:195], v[18:19], off offset:416
	global_load_dwordx4 v[196:199], v[18:19], off offset:448
	global_load_dwordx4 v[200:203], v[18:19], off offset:480
	ds_read_b128 v[46:49], v33
	ds_read_b128 v[50:53], v33 offset:32
	ds_read_b128 v[54:57], v33 offset:64
	ds_read_b128 v[58:61], v33 offset:96
	ds_read_b128 v[62:65], v33 offset:128
	ds_read_b128 v[66:69], v33 offset:160
	ds_read_b128 v[70:73], v33 offset:192
	ds_read_b128 v[74:77], v33 offset:224
	v_lshlrev_b32_e32 v16, 1, v31
	s_waitcnt vmcnt(8) lgkmcnt(0)
	v_mfma_f32_32x32x16_bf16 v[0:15], v[46:49], v[140:143], 0
	v_mfma_f32_32x32x16_bf16 v[0:15], v[50:53], v[144:147], v[0:15]
	v_mfma_f32_32x32x16_bf16 v[0:15], v[54:57], v[148:151], v[0:15]
	v_mfma_f32_32x32x16_bf16 v[0:15], v[58:61], v[152:155], v[0:15]
	v_mfma_f32_32x32x16_bf16 v[0:15], v[62:65], v[156:159], v[0:15]
	v_mfma_f32_32x32x16_bf16 v[0:15], v[66:69], v[160:163], v[0:15]
	v_mfma_f32_32x32x16_bf16 v[0:15], v[70:73], v[164:167], v[0:15]
	v_mfma_f32_32x32x16_bf16 v[0:15], v[74:77], v[168:171], v[0:15]
	ds_read_b128 v[46:49], v33 offset:256
	ds_read_b128 v[50:53], v33 offset:288
	ds_read_b128 v[54:57], v33 offset:320
	ds_read_b128 v[58:61], v33 offset:352
	ds_read_b128 v[62:65], v33 offset:384
	ds_read_b128 v[66:69], v33 offset:416
	ds_read_b128 v[70:73], v33 offset:448
	ds_read_b128 v[74:77], v33 offset:480
	v_lshl_add_u32 v18, v32, 2, s63
	v_cmp_gt_i32_e32 vcc, s29, v18
	s_waitcnt vmcnt(0) lgkmcnt(0)
	v_mfma_f32_32x32x16_bf16 v[0:15], v[46:49], v[172:175], v[0:15]
	v_mfma_f32_32x32x16_bf16 v[0:15], v[50:53], v[176:179], v[0:15]
	v_mfma_f32_32x32x16_bf16 v[0:15], v[54:57], v[180:183], v[0:15]
	v_mfma_f32_32x32x16_bf16 v[0:15], v[58:61], v[184:187], v[0:15]
	v_mfma_f32_32x32x16_bf16 v[0:15], v[62:65], v[188:191], v[0:15]
	v_mfma_f32_32x32x16_bf16 v[0:15], v[66:69], v[192:195], v[0:15]
	v_mfma_f32_32x32x16_bf16 v[0:15], v[70:73], v[196:199], v[0:15]
	v_mfma_f32_32x32x16_bf16 v[0:15], v[74:77], v[200:203], v[0:15]
	s_and_saveexec_b64 s[64:65], vcc
	s_cbranch_execz .LBB0_1064
	v_mul_hi_i32 v19, v18, s57
	v_add_u32_e32 v19, v19, v18
	v_lshrrev_b32_e32 v20, 31, v19
	v_ashrrev_i32_e32 v19, 7, v19
	v_add_u32_e32 v19, v19, v20
	v_mul_lo_u32 v20, v19, s7
	v_sub_u32_e32 v20, v18, v20
	v_ashrrev_i32_e32 v20, 1, v20
	v_lshl_add_u32 v20, v19, 7, v20
	v_ashrrev_i32_e32 v21, 31, v20
	v_lshlrev_b64 v[20:21], 8, v[20:21]
	v_lshl_add_u64 v[20:21], s[66:67], 0, v[20:21]
	s_mov_b32 s63, s15
	v_lshl_add_u64 v[20:21], v[20:21], 0, s[62:63]
	v_cvt_pk_bf16_f32 v0, v0, s0
	v_lshl_add_u64 v[20:21], v[20:21], 0, v[16:17]
	global_store_short v[20:21], v0, off
